# sample attention unit: small dependent loads (new-token k/v, k-norm gain, q-norm gains, sink) hoisted to the unit top ahead of the cache loads; store-draining vmcnt(0) waits gone
# speedup vs baseline: 1.0064x; 1.0000x over previous
; __device__ __forceinline__ void attn_sample_unit(const Args& a, LAS unsigned char* lds, int l, int b, int kvh, int tid) {
;     ...
;     const float* ck = a.in[I_CK] + ((size_t)l * DEC_B + b) * WIN * 128 + kvh * 64; const float* cv = a.in[I_CV] + ((size_t)l * DEC_B + b) * WIN * 128 + kvh * 64;
;     float* ko = a.out + O_KS + ((size_t)l * DEC_B + b) * WIN * 128 + kvh * 64; float* vo = a.out + O_VS + ((size_t)l * DEC_B + b) * WIN * 128 + kvh * 64;
;     const size_t zrow0 = (size_t)NTOK_P + b * DEC_T;
;     const int lane = tid & 63, r = lane & 15, qd = lane >> 4, t = r >> 2, h = kvh * 4 + (r & 3);
;     u32x4 qraw[2];
;     { const bf16_t* zq = Z + (zrow0 + t) * INC + ZQ + h * 64 + 8 * qd; qraw[0] = *(const u32x4*)zq; qraw[1] = *(const u32x4*)(zq + 32); }
;     {
;         f32x4 kv[4], vv[4];
; #pragma unroll
;         for (int k = 0; k < 4; ++k) { const int idx = tid + 512 * k, row = idx >> 4, c4 = idx & 15; kv[k] = *(const f32x4*)(ck + (size_t)row * 128 + c4 * 4); vv[k] = *(const f32x4*)(cv + (size_t)row * 128 + c4 * 4); }
;         for (int i = tid; i < (NKP - WIN - DEC_T) * 64; i += 512) { const int row = WIN + DEC_T + (i >> 6), d = i & 63; Ks[row * KST + d] = 0; Vt[d * VST + row] = 0; }
; #pragma unroll
;         for (int k = 0; k < 4; ++k) { const int idx = tid + 512 * k, row = idx >> 4, c4 = idx & 15;
;             u32x2 w; w.x = pk2(kv[k][0], kv[k][1]); w.y = pk2(kv[k][2], kv[k][3]); *(LAS u32x2*)(Ks + row * KST + c4 * 4) = w;
; #pragma unroll
;             for (int i = 0; i < 4; ++i) Vt[(c4 * 4 + i) * VST + row] = f2bf(vv[k][i]);
;             if (row >= DEC_T) { *(f32x4*)(ko + (size_t)(row - DEC_T) * 128 + c4 * 4) = kv[k]; *(f32x4*)(vo + (size_t)(row - DEC_T) * 128 + c4 * 4) = vv[k]; } }
;         if (tid < 256) { const int t2 = tid >> 6, d = tid & 63; const bf16_t* zr = Z + (zrow0 + t2) * INC + kvh * 64 + d;
;             const float kr = bf2f(zr[ZK]), vr = bf2f(zr[ZV]); const float sq = wave_sum(kr * kr); const float kn = kr * rsqrtf(sq * (1.f / 64.f) + EPS) * gk[d];
;             Ks[(WIN + t2) * KST + d] = f2bf(kn); Vt[d * VST + WIN + t2] = zr[ZV]; ko[(size_t)(WIN - DEC_T + t2) * 128 + d] = kn; vo[(size_t)(WIN - DEC_T + t2) * 128 + d] = vr; }
;     }
;     __syncthreads();
;     if (tid < 64) {
;         const float cs = 0.125f * LOG2E, sinkl = a.in[I_SINK][l * 8 + h] * LOG2E, slope = exp2f(-(float)(h + 1)) * LOG2E;
.LBB0_596:
	s_mul_i32 s0, s16, s12
	s_add_i32 s0, s0, s14
	s_ashr_i32 s10, s0, 1
	s_and_b32 s17, s0, 1
	s_ashr_i32 s1, s10, 31
	s_add_u32 s0, s10, s15
	s_addc_u32 s1, s1, 0
	s_lshl_b64 s[6:7], s[0:1], 16
	s_add_u32 s8, s52, s6
	s_addc_u32 s9, s53, s7
	s_lshl_b32 s11, s17, 8
	s_add_u32 s8, s8, s11
	s_addc_u32 s9, s9, 0
	s_add_u32 s6, s54, s6
	s_addc_u32 s7, s55, s7
	s_add_u32 s6, s6, s11
	s_addc_u32 s7, s7, 0
	s_lshl_b32 s10, s10, 2
	v_mov_b32_e32 v77, v184
	s_ashr_i32 s11, s10, 31
	s_add_u32 s10, s10, 0x4000
	s_waitcnt vmcnt(1)
	v_bfe_u32 v75, v77, 2, 2
	s_addc_u32 s11, s11, 0
	s_lshl_b32 s18, s17, 2
	v_or_b32_e32 v2, s10, v75
	v_mov_b64_e32 v[20:21], s[48:49]
	v_and_or_b32 v76, v77, 3, s18
	v_mad_u64_u32 v[20:21], s[18:19], v2, s87, v[20:21]
	v_mad_i32_i24 v21, s11, v215, v21
	v_lshlrev_b32_e32 v0, 7, v76
	v_lshl_add_u64 v[20:21], v[20:21], 0, v[0:1]
	v_and_b32_e32 v0, 48, v77
	v_lshl_add_u64 v[20:21], v[20:21], 0, v[0:1]
	v_lshlrev_b32_e32 v0, 2, v77
	v_and_b32_e32 v78, 60, v0
	v_ashrrev_i32_e32 v72, 4, v77
	v_lshlrev_b32_e32 v0, 2, v78
	v_ashrrev_i32_e32 v73, 31, v72
	v_add_u32_e32 v3, 0x200, v77
	v_lshl_add_u64 v[28:29], s[8:9], 0, v[0:1]
	v_lshl_add_u64 v[32:33], s[6:7], 0, v[0:1]
	v_lshlrev_b64 v[30:31], 9, v[72:73]
	v_ashrrev_i32_e32 v66, 4, v3
	v_lshl_add_u64 v[34:35], v[28:29], 0, v[30:31]
	v_lshl_add_u64 v[30:31], v[32:33], 0, v[30:31]
	v_ashrrev_i32_e32 v67, 31, v66
	v_add_u32_e32 v3, 0x400, v77
	v_bfe_u32 v142, v184, 6, 2
	v_or_b32_e32 v142, s10, v142
	v_mul_lo_u32 v142, v142, s87
	v_and_b32_e32 v143, 63, v184
	v_lshl_add_u32 v142, v143, 1, v142
	v_mov_b32_e32 v144, s17
	v_lshl_add_u32 v142, v144, 7, v142
	v_lshlrev_b32_e32 v145, 2, v143
	v_mov_b32_e32 v143, 0
	v_lshl_add_u64 v[142:143], s[48:49], 0, v[142:143]
	global_load_ushort v139, v[142:143], off offset:1024
	global_load_ushort v140, v[142:143], off offset:1280
	global_load_dword v141, v145, s[42:43]
	v_bfe_u32 v144, v184, 4, 2
	v_lshlrev_b32_e32 v144, 5, v144
	global_load_dwordx4 v[122:125], v144, s[44:45]
	global_load_dwordx4 v[126:129], v144, s[44:45] offset:16
	global_load_dwordx4 v[130:133], v144, s[44:45] offset:144
	global_load_dwordx4 v[134:137], v144, s[44:45] offset:128
	v_readlane_b32 s98, v252, 44
	v_readlane_b32 s99, v252, 45
	v_or_b32_e32 v146, s93, v76
	v_mov_b32_e32 v147, 0
	v_lshl_add_u64 v[146:147], v[146:147], 2, s[98:99]
	global_load_dword v138, v[146:147], off
	global_load_dwordx4 v[24:27], v[20:21], off
	s_nop 0
	global_load_dwordx4 v[20:23], v[20:21], off offset:64
	v_ashrrev_i32_e32 v64, 4, v3
	global_load_dwordx4 v[56:59], v[30:31], off
	v_lshlrev_b64 v[30:31], 9, v[66:67]
	global_load_dwordx4 v[52:55], v[34:35], off
	v_lshl_add_u64 v[34:35], v[28:29], 0, v[30:31]
	v_lshl_add_u64 v[30:31], v[32:33], 0, v[30:31]
	v_ashrrev_i32_e32 v65, 31, v64
	v_add_u32_e32 v3, 0x600, v77
	global_load_dwordx4 v[48:51], v[30:31], off
	v_lshlrev_b64 v[30:31], 9, v[64:65]
	v_ashrrev_i32_e32 v62, 4, v3
	global_load_dwordx4 v[44:47], v[34:35], off
	v_lshl_add_u64 v[34:35], v[28:29], 0, v[30:31]
	v_ashrrev_i32_e32 v63, 31, v62
	global_load_dwordx4 v[36:39], v[34:35], off
	v_lshlrev_b64 v[34:35], 9, v[62:63]
	v_lshl_add_u64 v[30:31], v[32:33], 0, v[30:31]
	v_lshl_add_u64 v[28:29], v[28:29], 0, v[34:35]
	v_lshl_add_u64 v[32:33], v[32:33], 0, v[34:35]
	global_load_dwordx4 v[40:43], v[30:31], off
	s_movk_i32 s6, 0x700
	global_load_dwordx4 v[32:35], v[32:33], off
	v_and_b32_e32 v67, 63, v77
	global_load_dwordx4 v[28:31], v[28:29], off
	v_mov_b32_e32 v3, s11
	v_cmp_gt_i32_e32 vcc, s6, v77
	s_and_saveexec_b64 s[6:7], vcc
	s_cbranch_execz .LBB0_599
	v_lshl_add_u32 v60, v67, 1, 0
	s_movk_i32 s8, 0x15e
	v_mad_u32_u24 v61, v67, s8, v60
	s_mov_b64 s[8:9], 0
	v_mov_b32_e32 v63, v77

; __device__ __forceinline__ float bf2f(unsigned short b) { return __uint_as_float(((unsigned)b) << 16); }
; __device__ __forceinline__ unsigned short f2bf(float f) { return (unsigned short)(pg8::cvt_pk_bf16(f, 0.f) & 0xffffu); }
; __device__ __forceinline__ void unpack8(const u32x4 w, float (&f)[8]) { f[0] = bflo(w.x); f[1] = bfhi(w.x); f[2] = bflo(w.y); f[3] = bfhi(w.y); f[4] = bflo(w.z); f[5] = bfhi(w.z); f[6] = bflo(w.w); f[7] = bfhi(w.w); }
; __device__ __forceinline__ void attn_sample_unit(const Args& a, LAS unsigned char* lds, int l, int b, int kvh, int tid) {
;     ...
;         if (tid < 256) { const int t2 = tid >> 6, d = tid & 63; const bf16_t* zr = Z + (zrow0 + t2) * INC + kvh * 64 + d;
;             const float kr = bf2f(zr[ZK]), vr = bf2f(zr[ZV]); const float sq = wave_sum(kr * kr); const float kn = kr * rsqrtf(sq * (1.f / 64.f) + EPS) * gk[d];
;             Ks[(WIN + t2) * KST + d] = f2bf(kn); Vt[d * VST + WIN + t2] = zr[ZV]; ko[(size_t)(WIN - DEC_T + t2) * 128 + d] = kn; vo[(size_t)(WIN - DEC_T + t2) * 128 + d] = vr; }
;     }
;     __syncthreads();
;     if (tid < 64) {
;         const float cs = 0.125f * LOG2E, sinkl = a.in[I_SINK][l * 8 + h] * LOG2E, slope = exp2f(-(float)(h + 1)) * LOG2E;
;         bf16x8 qf[2];
;         {   float x[16]; { float t8[8]; unpack8(qraw[0], t8);
; #pragma unroll
;                 for (int k = 0; k < 8; ++k) x[k] = t8[k];
;                 unpack8(qraw[1], t8);
; #pragma unroll
;                 for (int k = 0; k < 8; ++k) x[8 + k] = t8[k]; }
;             float sq = 0.f;
; #pragma unroll
;             for (int k = 0; k < 16; ++k) sq += x[k] * x[k];
;             sq += __shfl_xor(sq, 16); sq += __shfl_xor(sq, 32);
;             const float rs = rsqrtf(sq * (1.f / 64.f) + EPS) * cs;
; #pragma unroll
;             for (int k = 0; k < 16; ++k) x[k] = x[k] * rs * gq[(k >> 3) * 32 + 8 * qd + (k & 7)];
; #pragma unroll
.LBB0_607:
	s_or_b64 exec, exec, s[8:9]
	s_movk_i32 s8, 0x100
	v_cmp_gt_i32_e32 vcc, s8, v77
	s_and_saveexec_b64 s[8:9], vcc
	s_cbranch_execz .LBB0_609
	v_ashrrev_i32_e32 v28, 6, v77
	v_ashrrev_i32_e32 v29, 31, v28
	v_lshl_add_u64 v[30:31], s[10:11], 0, v[28:29]
	v_mov_b64_e32 v[32:33], s[48:49]
	v_mad_u64_u32 v[32:33], s[10:11], v30, s87, v[32:33]
	v_mad_i32_i24 v33, v31, s87, v33
	s_lshl_b32 s26, s17, 1
	v_lshl_add_u64 v[30:31], v[32:33], 0, s[26:27]
	v_lshlrev_b32_e32 v0, 1, v67
	v_lshl_add_u64 v[30:31], v[30:31], 0, v[0:1]
	v_and_b32_e32 v35, 64, v216
	v_add_u32_e32 v35, 64, v35
	v_xor_b32_e32 v36, 1, v216
	v_cmp_lt_i32_e32 vcc, v36, v35
	s_mov_b64 s[10:11], 0xf800
	v_lshlrev_b32_e32 v33, 16, v139
	v_cndmask_b32_e32 v36, v216, v36, vcc
	v_mul_f32_e32 v34, v33, v33
	v_lshlrev_b32_e32 v36, 2, v36
	ds_bpermute_b32 v34, v36, v34
	v_xor_b32_e32 v36, 2, v216
	v_cmp_lt_i32_e32 vcc, v36, v35
	s_waitcnt lgkmcnt(0)
	v_fmac_f32_e32 v34, v33, v33
	v_cndmask_b32_e32 v36, v216, v36, vcc
	v_lshlrev_b32_e32 v36, 2, v36
	ds_bpermute_b32 v36, v36, v34
	s_waitcnt lgkmcnt(0)
	v_add_f32_e32 v34, v34, v36
	v_xor_b32_e32 v36, 4, v216
	v_cmp_lt_i32_e32 vcc, v36, v35
	v_lshlrev_b32_e32 v32, 16, v140
	v_cndmask_b32_e32 v36, v216, v36, vcc
	v_lshlrev_b32_e32 v36, 2, v36
	ds_bpermute_b32 v36, v36, v34
	s_waitcnt lgkmcnt(0)
	v_add_f32_e32 v34, v34, v36
	v_xor_b32_e32 v36, 8, v216
	v_cmp_lt_i32_e32 vcc, v36, v35
	s_nop 1
	v_cndmask_b32_e32 v36, v216, v36, vcc
	v_lshlrev_b32_e32 v36, 2, v36
	ds_bpermute_b32 v36, v36, v34
	s_waitcnt lgkmcnt(0)
	v_add_f32_e32 v34, v34, v36
	v_xor_b32_e32 v36, 16, v216
	v_cmp_lt_i32_e32 vcc, v36, v35
	s_nop 1
	v_cndmask_b32_e32 v36, v216, v36, vcc
	v_lshlrev_b32_e32 v36, 2, v36
	ds_bpermute_b32 v36, v36, v34
	s_waitcnt lgkmcnt(0)
	v_add_f32_e32 v34, v34, v36
	v_xor_b32_e32 v36, 32, v216
	v_cmp_lt_i32_e32 vcc, v36, v35
	s_nop 1
	v_cndmask_b32_e32 v35, v216, v36, vcc
	v_lshlrev_b32_e32 v35, 2, v35
	ds_bpermute_b32 v35, v35, v34
	v_mul_lo_u32 v36, v28, s88
	v_add3_u32 v0, 0, v36, v0
	s_waitcnt lgkmcnt(0)
	v_add_f32_e32 v34, v34, v35
	v_fmamk_f32 v34, v34, 0x3c800000, v185
	v_cmp_gt_f32_e32 vcc, s86, v34
	v_mul_f32_e32 v35, 0x4b800000, v34
	s_nop 0
	v_cndmask_b32_e32 v34, v34, v35, vcc
	v_rsq_f32_e32 v34, v34
	s_nop 0
	v_mul_f32_e32 v35, 0x45800000, v34
	v_cndmask_b32_e32 v34, v34, v35, vcc
	v_mul_f32_e32 v33, v34, v33
	v_lshlrev_b32_e32 v34, 2, v67
	v_mul_f32_e32 v33, v141, v33
	v_cvt_pk_bf16_f32 v35, v33, v1
	ds_write_b16 v0, v35 offset:18432
	v_mov_b32_e32 v0, v140
	v_lshlrev_b32_e32 v31, 1, v28
	v_lshlrev_b64 v[28:29], 9, v[28:29]
	v_mul_u32_u24_e32 v30, 0x160, v67
	v_or_b32_e32 v28, v28, v34
	v_add3_u32 v30, 0, v30, v31
	v_lshl_add_u64 v[28:29], v[28:29], 0, s[10:11]
	ds_write_b16 v30, v0 offset:23296
	v_lshl_add_u64 v[30:31], s[6:7], 0, v[28:29]
	v_lshl_add_u64 v[28:29], s[0:1], 0, v[28:29]
	global_store_dword v[30:31], v33, off
	global_store_dword v[28:29], v32, off
.LBB0_609:
	s_or_b64 exec, exec, s[8:9]
	v_cmp_gt_i32_e32 vcc, 64, v77
	s_waitcnt lgkmcnt(0)
	s_barrier
	s_and_saveexec_b64 s[6:7], vcc
	s_cbranch_execz .LBB0_595
	v_lshlrev_b32_e32 v0, 2, v60
	v_mov_b64_e32 v[30:31], v[122:123]
	v_mov_b64_e32 v[32:33], v[124:125]
	v_mov_b64_e32 v[34:35], v[126:127]
	v_mov_b64_e32 v[36:37], v[128:129]
	v_mov_b64_e32 v[38:39], v[130:131]
	v_mov_b64_e32 v[40:41], v[132:133]
	v_mov_b64_e32 v[42:43], v[134:135]
	v_mov_b64_e32 v[44:45], v[136:137]
	v_and_b32_e32 v55, 0xffff0000, v24
	v_lshlrev_b32_e32 v54, 16, v24
	v_mul_f32_e32 v29, v55, v55
	v_lshlrev_b32_e32 v56, 16, v25
	v_fmac_f32_e32 v29, v54, v54
	v_and_b32_e32 v57, 0xffff0000, v25
	v_fmac_f32_e32 v29, v56, v56
	v_lshlrev_b32_e32 v58, 16, v26
	v_fmac_f32_e32 v29, v57, v57
	v_and_b32_e32 v59, 0xffff0000, v26
	v_and_b32_e32 v28, 64, v216
	v_fmac_f32_e32 v29, v58, v58
	v_lshlrev_b32_e32 v62, 16, v27
	v_xor_b32_e32 v0, 16, v216
	v_add_u32_e32 v66, 64, v28
	v_fmac_f32_e32 v29, v59, v59
	v_and_b32_e32 v64, 0xffff0000, v27
	v_and_b32_e32 v24, 0xffff0000, v20
	v_lshlrev_b32_e32 v25, 16, v20
	v_cmp_lt_i32_e32 vcc, v0, v66
	v_fmac_f32_e32 v29, v62, v62
	v_pk_mul_f32 v[46:47], v[24:25], v[24:25]
	v_cndmask_b32_e32 v0, v216, v0, vcc
	v_fmac_f32_e32 v29, v64, v64
	v_and_b32_e32 v20, 0xffff0000, v21
	v_lshlrev_b32_e32 v21, 16, v21
	v_lshlrev_b32_e32 v28, 2, v0
	v_add_f32_e32 v0, v47, v29
	v_pk_mul_f32 v[48:49], v[20:21], v[20:21]
	v_add_f32_e32 v0, v46, v0
	v_and_b32_e32 v26, 0xffff0000, v22
	v_lshlrev_b32_e32 v27, 16, v22
	v_add_f32_e32 v0, v49, v0
	v_pk_mul_f32 v[50:51], v[26:27], v[26:27]
	v_add_f32_e32 v0, v48, v0
	v_and_b32_e32 v22, 0xffff0000, v23
	v_lshlrev_b32_e32 v23, 16, v23
	v_add_f32_e32 v0, v51, v0
	v_pk_mul_f32 v[52:53], v[22:23], v[22:23]
	v_add_f32_e32 v0, v50, v0
	v_add_f32_e32 v0, v53, v0
	v_add_f32_e32 v0, v52, v0
	ds_bpermute_b32 v46, v28, v0
	v_xor_b32_e32 v29, 32, v216
	v_cmp_lt_i32_e32 vcc, v29, v66
	v_readlane_b32 s52, v252, 38
	v_readlane_b32 s58, v252, 44
	v_cndmask_b32_e32 v29, v216, v29, vcc
	v_lshlrev_b32_e32 v29, 2, v29
	s_waitcnt lgkmcnt(0)
	v_add_f32_e32 v0, v0, v46
	ds_bpermute_b32 v46, v29, v0
	v_readlane_b32 s59, v252, 45
	s_mov_b32 s0, 0x42fc0000
	v_lshlrev_b64 v[2:3], 10, v[2:3]
	v_lshl_add_u64 v[2:3], s[36:37], 0, v[2:3]
	s_waitcnt lgkmcnt(0)
; #define LAS __attribute__((address_space(3)))
; __device__ __forceinline__ unsigned pk2(float lo, float hi) { return pg8::cvt_pk_bf16(lo, hi); }
; __device__ __forceinline__ void attn_sample_unit(const Args& a, LAS unsigned char* lds, int l, int b, int kvh, int tid) {
;     ...
;         const float cs = 0.125f * LOG2E, sinkl = a.in[I_SINK][l * 8 + h] * LOG2E, slope = exp2f(-(float)(h + 1)) * LOG2E;
;     ...
;             const float rs = rsqrtf(sq * (1.f / 64.f) + EPS) * cs;
; #pragma unroll
;             for (int k = 0; k < 16; ++k) x[k] = x[k] * rs * gq[(k >> 3) * 32 + 8 * qd + (k & 7)];
; #pragma unroll
;             for (int s = 0; s < 2; ++s) { u32x4 w; w.x = pk2(x[8 * s], x[8 * s + 1]); w.y = pk2(x[8 * s + 2], x[8 * s + 3]); w.z = pk2(x[8 * s + 4], x[8 * s + 5]); w.w = pk2(x[8 * s + 6], x[8 * s + 7]);
;                 qf[s] = __builtin_bit_cast(bf16x8, w); } }
;         f32x4 S[NKP / 16]; float mx = -1e30f;
; #pragma unroll
;         for (int T = 0; T < NKP / 16; ++T) {
;             const bf16x8 k0 = *(const LAS bf16x8*)(Ks + (16 * T + r) * KST + 8 * qd), k1 = *(const LAS bf16x8*)(Ks + (16 * T + r) * KST + 32 + 8 * qd);
;             S[T] = __builtin_amdgcn_mfma_f32_16x16x32_bf16(k0, qf[0], (f32x4){0.f, 0.f, 0.f, 0.f}, 0, 0, 0); S[T] = __builtin_amdgcn_mfma_f32_16x16x32_bf16(k1, qf[1], S[T], 0, 0, 0); }
; #pragma unroll
	v_add_f32_e32 v0, v0, v46
	v_fmamk_f32 v0, v0, 0x3c800000, v185
	v_mul_f32_e32 v46, 0x4b800000, v0
	v_cmp_gt_f32_e32 vcc, s86, v0
	v_readlane_b32 s53, v252, 39
	v_readlane_b32 s54, v252, 40
	v_cndmask_b32_e32 v0, v0, v46, vcc
	v_rsq_f32_e32 v48, v0
	v_or_b32_e32 v0, s93, v76
	v_lshl_add_u64 v[46:47], v[0:1], 2, s[58:59]
	v_mov_b32_e32 v0, v138
	v_mul_f32_e32 v46, 0x45800000, v48
	v_cndmask_b32_e32 v46, v48, v46, vcc
	v_mul_f32_e32 v46, 0x3e38aa3b, v46
	v_mul_f32_e32 v24, v46, v24
	v_mul_f32_e32 v20, v46, v20
	v_mul_f32_e32 v47, v46, v54
	v_mul_f32_e32 v48, v46, v55
	v_mul_f32_e32 v49, v46, v56
	v_mul_f32_e32 v50, v46, v57
	v_mul_f32_e32 v51, v46, v58
	v_mul_f32_e32 v52, v46, v59
	v_mul_f32_e32 v30, v30, v47
	v_mul_f32_e32 v31, v31, v48
	v_mul_f32_e32 v24, v43, v24
	v_mul_f32_e32 v43, v20, v45
	v_mul_f32_e32 v20, v46, v27
	v_mul_f32_e32 v27, v20, v38
	v_mul_f32_e32 v20, v46, v26
	v_mul_f32_e32 v26, v20, v39
	v_mul_f32_e32 v20, v46, v23
	v_mul_f32_e32 v38, v20, v40
	v_mul_f32_e32 v20, v46, v22
	v_mul_f32_e32 v53, v46, v62
	v_mul_f32_e32 v54, v46, v64
	v_mul_f32_e32 v25, v46, v25
	v_mul_f32_e32 v39, v20, v41
	v_cvt_pk_bf16_f32 v20, v30, v31
	v_mul_u32_u24_e32 v30, 0x90, v63
	v_lshlrev_b32_e32 v31, 1, v60
	v_mul_f32_e32 v32, v32, v49
	v_mul_f32_e32 v33, v33, v50
	v_mul_f32_e32 v34, v34, v51
	v_mul_f32_e32 v35, v35, v52
	v_mul_f32_e32 v36, v36, v53
	v_mul_f32_e32 v37, v37, v54
	v_mul_f32_e32 v25, v42, v25
	v_mul_f32_e32 v21, v46, v21
	v_add3_u32 v58, 0, v30, v31
	v_mul_f32_e32 v42, v21, v44
	v_cvt_pk_bf16_f32 v21, v32, v33
	v_cvt_pk_bf16_f32 v22, v34, v35
	v_cvt_pk_bf16_f32 v23, v36, v37
	v_cvt_pk_bf16_f32 v24, v25, v24
	v_cvt_pk_bf16_f32 v25, v42, v43
	v_cvt_pk_bf16_f32 v26, v27, v26
	v_cvt_pk_bf16_f32 v27, v38, v39
	ds_read_b128 v[30:33], v58
	ds_read_b128 v[34:37], v58 offset:64
	s_waitcnt lgkmcnt(1)
	v_mfma_f32_16x16x32_bf16 v[30:33], v[30:33], v[20:23], 0
	ds_read_b128 v[38:41], v58 offset:2304
	ds_read_b128 v[42:45], v58 offset:4608
	ds_read_b128 v[46:49], v58 offset:6912
	s_waitcnt lgkmcnt(3)
	v_mfma_f32_16x16x32_bf16 v[30:33], v[34:37], v[24:27], v[30:33]
	ds_read_b128 v[34:37], v58 offset:2368
	ds_read_b128 v[50:53], v58 offset:9216
	ds_read_b128 v[54:57], v58 offset:11520
	s_waitcnt lgkmcnt(5)
	v_mfma_f32_16x16x32_bf16 v[38:41], v[38:41], v[20:23], 0
	ds_read_b128 v[66:69], v58 offset:13824
	ds_read_b128 v[70:73], v58 offset:16128
	ds_read_b128 v[78:81], v58 offset:18432
	s_waitcnt lgkmcnt(5)
	v_mfma_f32_16x16x32_bf16 v[34:37], v[34:37], v[24:27], v[38:41]
	v_add_u32_e32 v59, 1, v76
	v_cvt_f32_ubyte0_e32 v59, v59
	v_cmp_lt_f32_e32 vcc, s0, v59
	ds_read_b128 v[38:41], v58 offset:4672
	v_mfma_f32_16x16x32_bf16 v[42:45], v[42:45], v[20:23], 0
	v_lshlrev_b32_e32 v62, 2, v65
	s_mov_b32 s0, 0xf149f2ca
	v_readlane_b32 s55, v252, 41
	s_waitcnt lgkmcnt(0)
	v_mfma_f32_16x16x32_bf16 v[38:41], v[38:41], v[24:27], v[42:45]
	s_nop 2
	ds_read_b128 v[42:45], v58 offset:6976
	v_readlane_b32 s56, v252, 42
	v_readlane_b32 s57, v252, 43
	v_mfma_f32_16x16x32_bf16 v[46:49], v[46:49], v[20:23], 0
	v_readlane_b32 s60, v252, 46
	v_readlane_b32 s61, v252, 47
	v_readlane_b32 s62, v252, 48
	s_waitcnt lgkmcnt(0)
	v_mfma_f32_16x16x32_bf16 v[42:45], v[42:45], v[24:27], v[46:49]
	v_readlane_b32 s63, v252, 49
	s_nop 1
	ds_read_b128 v[46:49], v58 offset:9280
	v_readlane_b32 s64, v252, 50
	v_mfma_f32_16x16x32_bf16 v[50:53], v[50:53], v[20:23], 0
	v_readlane_b32 s65, v252, 51
	v_readlane_b32 s66, v252, 52
	v_readlane_b32 s67, v252, 53
	s_waitcnt lgkmcnt(0)
	v_mfma_f32_16x16x32_bf16 v[46:49], v[46:49], v[24:27], v[50:53]
	v_readlane_b32 s52, v252, 0
	s_nop 1
	ds_read_b128 v[50:53], v58 offset:11584
	v_readlane_b32 s53, v252, 1
	v_mfma_f32_16x16x32_bf16 v[54:57], v[54:57], v[20:23], 0
	v_readlane_b32 s54, v252, 2
	v_readlane_b32 s55, v252, 3
	v_readlane_b32 s56, v252, 4
	s_waitcnt lgkmcnt(0)
	v_mfma_f32_16x16x32_bf16 v[50:53], v[50:53], v[24:27], v[54:57]
	v_readlane_b32 s57, v252, 5
	s_nop 1
	ds_read_b128 v[54:57], v58 offset:13888
	v_readlane_b32 s58, v252, 6
	v_mfma_f32_16x16x32_bf16 v[66:69], v[66:69], v[20:23], 0
	v_readlane_b32 s59, v252, 7
	v_readlane_b32 s60, v252, 8
	v_readlane_b32 s61, v252, 9
	s_waitcnt lgkmcnt(0)
	v_mfma_f32_16x16x32_bf16 v[54:57], v[54:57], v[24:27], v[66:69]
	v_readlane_b32 s62, v252, 10
	s_nop 1
	ds_read_b128 v[66:69], v58 offset:16192
	v_readlane_b32 s63, v252, 11
	v_mfma_f32_16x16x32_bf16 v[70:73], v[70:73], v[20:23], 0
	s_mov_b64 s[52:53], s[56:57]
	s_mov_b64 s[54:55], s[58:59]
	v_readlane_b32 s64, v252, 12
	s_waitcnt lgkmcnt(0)
	v_mfma_f32_16x16x32_bf16 v[66:69], v[66:69], v[24:27], v[70:73]
	v_readlane_b32 s65, v252, 13
	s_nop 1
	ds_read_b128 v[70:73], v58 offset:18496
	v_mov_b32_e32 v58, 0x42800000
	v_cndmask_b32_e32 v58, 0, v58, vcc
	v_sub_f32_e32 v58, v58, v59
	v_exp_f32_e32 v58, v58
	v_mfma_f32_16x16x32_bf16 v[20:23], v[78:81], v[20:23], 0
	v_not_b32_e32 v59, 63
	v_cndmask_b32_e32 v59, 0, v59, vcc
	v_ldexp_f32 v58, v58, v59
	v_or_b32_e32 v59, 0x80, v75
	v_sub_u32_e32 v64, v59, v62
	s_waitcnt lgkmcnt(0)
; __device__ __forceinline__ void attn_sample_unit(const Args& a, LAS unsigned char* lds, int l, int b, int kvh, int tid) {
;     ...
; #pragma unroll
;         for (int T = 0; T < NKP / 16; ++T)
; #pragma unroll
;             for (int i = 0; i < 4; ++i) { const int dist = WIN + t - (16 * T + 4 * qd + i);
;                 const float s = (unsigned)dist <= (unsigned)WIN ? S[T][i] - slope * (float)dist : -1e30f; S[T][i] = s; mx = fmaxf(mx, s); }
;         mx = fmaxf(mx, __shfl_xor(mx, 16)); mx = fmaxf(mx, __shfl_xor(mx, 32)); mx = fmaxf(mx, sinkl);
	v_mfma_f32_16x16x32_bf16 v[70:73], v[70:73], v[24:27], v[20:23]
	v_mul_f32_e32 v58, 0x3fb8aa3b, v58
	v_cmp_gt_u32_e32 vcc, s81, v64
	v_mov_b32_e32 v79, 0xf149f2ca
	v_cvt_f32_ubyte0_e32 v20, v64
	v_fma_f32 v20, -v58, v20, v30
	v_cndmask_b32_e32 v65, v79, v20, vcc
	v_xad_u32 v20, v62, -1, v59
	v_cvt_f32_ubyte0_e32 v21, v20
	v_cmp_gt_u32_e32 vcc, s81, v20
	v_or_b32_e32 v20, 2, v62
	v_fma_f32 v21, -v58, v21, v31
	v_sub_u32_e32 v20, v59, v20
	v_cndmask_b32_e32 v74, v79, v21, vcc
	v_cvt_f32_ubyte0_e32 v21, v20
	v_fma_f32 v21, -v58, v21, v32
	v_cmp_gt_u32_e32 vcc, s81, v20
	v_add_u32_e32 v20, -3, v64
	v_cvt_f32_u32_e32 v23, v20
	v_cndmask_b32_e32 v76, v79, v21, vcc
	v_add_u32_e32 v20, -16, v64
	v_subrev_u32_e32 v21, 17, v64
	v_cvt_f32_u32_e32 v21, v21
	v_cvt_f32_u32_e32 v20, v20
	v_max_f32_e32 v22, 0xf149f2ca, v65
	v_max3_f32 v24, v22, v74, v76
	v_fma_f32 v77, -v58, v23, v33
	v_pk_fma_f32 v[30:31], v[58:59], v[20:21], v[34:35] op_sel_hi:[0,1,1] neg_lo:[1,0,0] neg_hi:[1,0,0]
	v_subrev_u32_e32 v20, 18, v64
	v_subrev_u32_e32 v21, 19, v64
	v_cvt_f32_u32_e32 v21, v21
	v_cvt_f32_u32_e32 v20, v20
	v_subrev_u32_e32 v22, 32, v64
	v_subrev_u32_e32 v23, 33, v64
	v_cvt_f32_u32_e32 v23, v23
	v_cvt_f32_u32_e32 v22, v22
	v_pk_fma_f32 v[32:33], v[58:59], v[20:21], v[36:37] op_sel_hi:[0,1,1] neg_lo:[1,0,0] neg_hi:[1,0,0]
	v_subrev_u32_e32 v20, 34, v64
	v_subrev_u32_e32 v21, 35, v64
	v_cvt_f32_u32_e32 v21, v21
	v_cvt_f32_u32_e32 v20, v20
	v_pk_fma_f32 v[34:35], v[58:59], v[22:23], v[38:39] op_sel_hi:[0,1,1] neg_lo:[1,0,0] neg_hi:[1,0,0]
	v_subrev_u32_e32 v22, 48, v64
	v_subrev_u32_e32 v23, 49, v64
	v_cvt_f32_u32_e32 v23, v23
	v_cvt_f32_u32_e32 v22, v22
	v_pk_fma_f32 v[36:37], v[58:59], v[20:21], v[40:41] op_sel_hi:[0,1,1] neg_lo:[1,0,0] neg_hi:[1,0,0]
	v_subrev_u32_e32 v20, 50, v64
	v_subrev_u32_e32 v21, 51, v64
	v_cvt_f32_u32_e32 v21, v21
	v_cvt_f32_u32_e32 v20, v20
	v_pk_fma_f32 v[38:39], v[58:59], v[22:23], v[42:43] op_sel_hi:[0,1,1] neg_lo:[1,0,0] neg_hi:[1,0,0]
	v_subrev_u32_e32 v22, 64, v64
	v_add_u32_e32 v23, 0xffffffbf, v64
	v_cvt_f32_u32_e32 v23, v23
	v_cvt_f32_u32_e32 v22, v22
	v_pk_fma_f32 v[40:41], v[58:59], v[20:21], v[44:45] op_sel_hi:[0,1,1] neg_lo:[1,0,0] neg_hi:[1,0,0]
	v_add_u32_e32 v20, 0xffffffbe, v64
	v_add_u32_e32 v21, 0xffffffbd, v64
	v_cvt_f32_u32_e32 v21, v21
	v_cvt_f32_u32_e32 v20, v20
	v_pk_fma_f32 v[42:43], v[58:59], v[22:23], v[46:47] op_sel_hi:[0,1,1] neg_lo:[1,0,0] neg_hi:[1,0,0]
	v_add_u32_e32 v22, 0xffffffb0, v64
	v_add_u32_e32 v23, 0xffffffaf, v64
	v_max3_f32 v24, v24, v77, v30
	v_cvt_f32_u32_e32 v23, v23
	v_cvt_f32_u32_e32 v22, v22
	v_pk_fma_f32 v[44:45], v[58:59], v[20:21], v[48:49] op_sel_hi:[0,1,1] neg_lo:[1,0,0] neg_hi:[1,0,0]
	v_add_u32_e32 v20, 0xffffffae, v64
	v_add_u32_e32 v21, 0xffffffad, v64
	v_max3_f32 v24, v24, v31, v32
	v_cvt_f32_u32_e32 v21, v21
	v_cvt_f32_u32_e32 v20, v20
	v_max3_f32 v24, v24, v33, v34
	v_max3_f32 v24, v24, v35, v36
	v_max3_f32 v24, v24, v37, v38
	v_pk_fma_f32 v[46:47], v[58:59], v[22:23], v[50:51] op_sel_hi:[0,1,1] neg_lo:[1,0,0] neg_hi:[1,0,0]
	v_add_u32_e32 v22, 0xffffffa0, v64
	v_add_u32_e32 v23, 0xffffff9f, v64
	v_max3_f32 v24, v24, v39, v40
	v_cvt_f32_u32_e32 v23, v23
	v_cvt_f32_u32_e32 v22, v22
	v_pk_fma_f32 v[48:49], v[58:59], v[20:21], v[52:53] op_sel_hi:[0,1,1] neg_lo:[1,0,0] neg_hi:[1,0,0]
	v_add_u32_e32 v20, 0xffffff9e, v64
	v_add_u32_e32 v21, 0xffffff9d, v64
	v_max3_f32 v24, v24, v41, v42
	v_cvt_f32_u32_e32 v21, v21
	v_cvt_f32_u32_e32 v20, v20
	v_max3_f32 v24, v24, v43, v44
	v_max3_f32 v24, v24, v45, v46
	v_or_b32_e32 v78, 0x81, v62
	v_max3_f32 v24, v24, v47, v48
	v_pk_fma_f32 v[26:27], v[58:59], v[22:23], v[54:55] op_sel_hi:[0,1,1] neg_lo:[1,0,0] neg_hi:[1,0,0]
	v_add_u32_e32 v22, 0xffffff90, v64
	v_add_u32_e32 v23, 0xffffff8f, v64
	v_cvt_f32_u32_e32 v23, v23
	v_cvt_f32_u32_e32 v22, v22
	v_max3_f32 v50, v24, v49, v26
	v_pk_fma_f32 v[24:25], v[58:59], v[20:21], v[56:57] op_sel_hi:[0,1,1] neg_lo:[1,0,0] neg_hi:[1,0,0]
	v_add_u32_e32 v20, 0xffffff8e, v64
	v_add_u32_e32 v21, 0xffffff8d, v64
	v_sub_u32_e32 v53, v59, v78
	v_sub_u32_e32 v54, v75, v62
	v_max3_f32 v52, v50, v27, v24
	v_cvt_f32_u32_e32 v21, v21
	v_cvt_f32_u32_e32 v20, v20
	v_cvt_f32_u32_e32 v51, v53
	v_cvt_f32_u32_e32 v50, v54
	v_pk_fma_f32 v[22:23], v[58:59], v[22:23], v[66:67] op_sel_hi:[0,1,1] neg_lo:[1,0,0] neg_hi:[1,0,0]
	v_max3_f32 v52, v52, v25, v22
	v_pk_fma_f32 v[20:21], v[58:59], v[20:21], v[68:69] op_sel_hi:[0,1,1] neg_lo:[1,0,0] neg_hi:[1,0,0]
	v_pk_fma_f32 v[50:51], v[58:59], v[50:51], v[70:71] op_sel_hi:[0,1,1] neg_lo:[1,0,0] neg_hi:[1,0,0]
	v_cmp_gt_u32_e32 vcc, s81, v53
	v_max3_f32 v55, v52, v23, v20
	v_or_b32_e32 v52, 0x82, v62
	v_cndmask_b32_e32 v64, v79, v51, vcc
	v_or_b32_e32 v51, 0x83, v62
	v_sub_u32_e32 v56, v59, v51
	v_sub_u32_e32 v57, v59, v52
	v_cvt_f32_u32_e32 v53, v56
	v_cvt_f32_u32_e32 v52, v57
	v_cmp_gt_u32_e32 vcc, s81, v54
	v_readlane_b32 s66, v252, 14
	v_readlane_b32 s67, v252, 15
	v_cndmask_b32_e32 v59, v79, v50, vcc
	v_pk_fma_f32 v[50:51], v[58:59], v[52:53], v[72:73] op_sel_hi:[0,1,1] neg_lo:[1,0,0] neg_hi:[1,0,0]
	v_cmp_gt_u32_e32 vcc, s81, v56
	v_max3_f32 v54, v55, v21, v59
	v_mul_f32_e32 v52, 0x3fb8aa3b, v0
	v_cndmask_b32_e32 v58, v79, v51, vcc
	v_cmp_gt_u32_e32 vcc, s81, v57
	s_mov_b64 s[56:57], s[60:61]
	s_mov_b64 s[58:59], s[62:63]
	v_cndmask_b32_e32 v62, v79, v50, vcc
	v_max3_f32 v50, v54, v64, v62
	v_max3_f32 v50, v50, v58, s0
	ds_bpermute_b32 v51, v28, v50
	v_cmp_lt_f32_e32 vcc, s92, v65
	s_mov_b32 s0, 0x3fb8aa3b
	s_waitcnt lgkmcnt(0)
	v_max_f32_e32 v51, v51, v51
	v_max_f32_e32 v50, v50, v51
	ds_bpermute_b32 v51, v29, v50
	s_waitcnt lgkmcnt(0)
; #define LAS __attribute__((address_space(3)))
; __device__ __forceinline__ unsigned pk2(float lo, float hi) { return pg8::cvt_pk_bf16(lo, hi); }
; __device__ __forceinline__ void attn_sample_unit(const Args& a, LAS unsigned char* lds, int l, int b, int kvh, int tid) {
;     ...
;         mx = fmaxf(mx, __shfl_xor(mx, 16)); mx = fmaxf(mx, __shfl_xor(mx, 32)); mx = fmaxf(mx, sinkl);
;         float lsum = 0.f;
; #pragma unroll
;         for (int T = 0; T < NKP / 16; ++T)
; #pragma unroll
;             for (int i = 0; i < 4; ++i) { const float p = S[T][i] > -1e29f ? __builtin_amdgcn_exp2f(S[T][i] - mx) : 0.f; S[T][i] = p; lsum += p; }
;         f32x4 O[4];
; #pragma unroll
;         for (int dt = 0; dt < 4; ++dt) O[dt] = (f32x4){0.f, 0.f, 0.f, 0.f};
; #pragma unroll
;         for (int st = 0; st < NKP / 32; ++st) {
;             u32x4 w; w.x = pk2(S[2 * st][0], S[2 * st][1]); w.y = pk2(S[2 * st][2], S[2 * st][3]); w.z = pk2(S[2 * st + 1][0], S[2 * st + 1][1]); w.w = pk2(S[2 * st + 1][2], S[2 * st + 1][3]);
;             const bf16x8 pf = __builtin_bit_cast(bf16x8, w);
; #pragma unroll
;             for (int dt = 0; dt < 4; ++dt) { const u32x2 lo = *(const LAS u32x2*)(Vt + (dt * 16 + r) * VST + 32 * st + 4 * qd), hi = *(const LAS u32x2*)(Vt + (dt * 16 + r) * VST + 32 * st + 16 + 4 * qd);
;                 O[dt] = __builtin_amdgcn_mfma_f32_16x16x32_bf16(__builtin_bit_cast(bf16x8, (u32x4){lo.x, lo.y, hi.x, hi.y}), pf, O[dt], 0, 0, 0); }
	v_max3_f32 v66, v50, v51, v52
	v_sub_f32_e32 v50, v65, v66
	v_exp_f32_e32 v50, v50
	v_sub_f32_e32 v52, v74, v66
	v_exp_f32_e32 v52, v52
	v_sub_f32_e32 v53, v76, v66
	v_exp_f32_e32 v53, v53
	v_sub_f32_e32 v54, v77, v66
	v_exp_f32_e32 v54, v54
	v_sub_f32_e32 v55, v30, v66
	v_cndmask_b32_e32 v50, 0, v50, vcc
	v_cmp_lt_f32_e32 vcc, s92, v74
	v_exp_f32_e32 v55, v55
	v_add_f32_e32 v51, 0, v50
	v_cndmask_b32_e32 v52, 0, v52, vcc
	v_cmp_lt_f32_e32 vcc, s92, v76
	v_add_f32_e32 v51, v52, v51
	v_sub_f32_e32 v56, v32, v66
	v_cndmask_b32_e32 v53, 0, v53, vcc
	v_cmp_lt_f32_e32 vcc, s92, v77
	v_add_f32_e32 v51, v53, v51
	v_exp_f32_e32 v56, v56
	v_cndmask_b32_e32 v54, 0, v54, vcc
	v_cmp_lt_f32_e32 vcc, s92, v30
	v_add_f32_e32 v51, v54, v51
	v_fma_f32 v0, v0, s0, -v66
	v_cndmask_b32_e32 v55, 0, v55, vcc
	v_add_f32_e32 v30, v55, v51
	v_sub_f32_e32 v51, v31, v66
	v_exp_f32_e32 v51, v51
	v_cmp_lt_f32_e32 vcc, s92, v31
	v_sub_f32_e32 v31, v33, v66
	v_exp_f32_e32 v31, v31
	v_cndmask_b32_e32 v51, 0, v51, vcc
	v_cmp_lt_f32_e32 vcc, s92, v32
	v_sub_f32_e32 v32, v34, v66
	v_exp_f32_e32 v32, v32
	v_cndmask_b32_e32 v56, 0, v56, vcc
	v_cmp_lt_f32_e32 vcc, s92, v33
	v_add_f32_e32 v30, v51, v30
	v_add_f32_e32 v30, v56, v30
	v_cndmask_b32_e32 v33, 0, v31, vcc
	v_cmp_lt_f32_e32 vcc, s92, v34
	v_sub_f32_e32 v31, v35, v66
	v_exp_f32_e32 v31, v31
	v_cndmask_b32_e32 v57, 0, v32, vcc
	v_sub_f32_e32 v32, v36, v66
	v_exp_f32_e32 v32, v32
	v_cmp_lt_f32_e32 vcc, s92, v35
	v_add_f32_e32 v30, v33, v30
	v_add_f32_e32 v30, v57, v30
	v_cndmask_b32_e32 v65, 0, v31, vcc
	v_cmp_lt_f32_e32 vcc, s92, v36
	v_sub_f32_e32 v31, v37, v66
	v_exp_f32_e32 v31, v31
	v_cndmask_b32_e32 v67, 0, v32, vcc
	v_sub_f32_e32 v32, v38, v66
	v_exp_f32_e32 v32, v32
	v_cmp_lt_f32_e32 vcc, s92, v37
	v_add_f32_e32 v30, v65, v30
	v_add_f32_e32 v30, v67, v30
	v_cndmask_b32_e32 v68, 0, v31, vcc
	v_cmp_lt_f32_e32 vcc, s92, v38
	v_sub_f32_e32 v31, v39, v66
	v_exp_f32_e32 v31, v31
	v_cndmask_b32_e32 v69, 0, v32, vcc
	v_sub_f32_e32 v32, v40, v66
	v_exp_f32_e32 v32, v32
	v_cmp_lt_f32_e32 vcc, s92, v39
	v_add_f32_e32 v30, v68, v30
	v_add_f32_e32 v30, v69, v30
	v_cndmask_b32_e32 v70, 0, v31, vcc
	v_cmp_lt_f32_e32 vcc, s92, v40
	v_sub_f32_e32 v31, v41, v66
	v_exp_f32_e32 v31, v31
	v_cndmask_b32_e32 v71, 0, v32, vcc
	v_sub_f32_e32 v32, v42, v66
	v_exp_f32_e32 v32, v32
	v_cmp_lt_f32_e32 vcc, s92, v41
	v_add_f32_e32 v30, v70, v30
	v_add_f32_e32 v30, v71, v30
	v_cndmask_b32_e32 v72, 0, v31, vcc
	v_cmp_lt_f32_e32 vcc, s92, v42
	v_sub_f32_e32 v31, v43, v66
	v_exp_f32_e32 v31, v31
	v_cndmask_b32_e32 v73, 0, v32, vcc
	v_sub_f32_e32 v32, v44, v66
	v_exp_f32_e32 v32, v32
	v_cmp_lt_f32_e32 vcc, s92, v43
	v_add_f32_e32 v30, v72, v30
	v_add_f32_e32 v30, v73, v30
	v_cndmask_b32_e32 v74, 0, v31, vcc
	v_cmp_lt_f32_e32 vcc, s92, v44
	v_sub_f32_e32 v31, v45, v66
	v_exp_f32_e32 v31, v31
	v_cndmask_b32_e32 v75, 0, v32, vcc
	v_sub_f32_e32 v32, v46, v66
	v_exp_f32_e32 v32, v32
	v_cmp_lt_f32_e32 vcc, s92, v45
	v_add_f32_e32 v30, v74, v30
	v_add_f32_e32 v30, v75, v30
	v_cndmask_b32_e32 v76, 0, v31, vcc
	v_cmp_lt_f32_e32 vcc, s92, v46
	v_sub_f32_e32 v31, v47, v66
	v_exp_f32_e32 v31, v31
	v_cndmask_b32_e32 v77, 0, v32, vcc
	v_sub_f32_e32 v32, v48, v66
	v_exp_f32_e32 v32, v32
	v_cmp_lt_f32_e32 vcc, s92, v47
	v_add_f32_e32 v30, v76, v30
	v_add_f32_e32 v30, v77, v30
	v_cndmask_b32_e32 v78, 0, v31, vcc
	v_cmp_lt_f32_e32 vcc, s92, v48
	v_sub_f32_e32 v31, v49, v66
	v_exp_f32_e32 v31, v31
	v_cndmask_b32_e32 v79, 0, v32, vcc
	v_sub_f32_e32 v32, v26, v66
	v_exp_f32_e32 v32, v32
	v_add_f32_e32 v30, v78, v30
	v_cmp_lt_f32_e32 vcc, s92, v49
	v_mul_u32_u24_e32 v34, 0x160, v63
	v_add_f32_e32 v30, v79, v30
	v_cndmask_b32_e32 v80, 0, v31, vcc
	v_cmp_lt_f32_e32 vcc, s92, v26
	v_add3_u32 v46, 0, v34, v60
	v_sub_f32_e32 v38, v27, v66
	v_add_f32_e32 v30, v80, v30
	v_cndmask_b32_e32 v81, 0, v32, vcc
	v_add_u32_e32 v63, 0x5800, v46
	v_exp_f32_e32 v42, v38
	v_add_f32_e32 v26, v81, v30
	v_cvt_pk_bf16_f32 v30, v50, v52
	v_cvt_pk_bf16_f32 v31, v53, v54
	v_cvt_pk_bf16_f32 v32, v55, v51
	v_cvt_pk_bf16_f32 v33, v56, v33
	ds_read2_b64 v[34:37], v63 offset0:64 offset1:68
	v_add_u32_e32 v82, 0x7000, v46
	v_cmp_lt_f32_e32 vcc, s92, v27
	v_add_u32_e32 v84, 0x8000, v46
	v_add_u32_e32 v85, 0x9800, v46
	ds_read2_b64 v[38:41], v82 offset1:4
	v_cndmask_b32_e32 v83, 0, v42, vcc
	ds_read2_b64 v[42:45], v84 offset0:192 offset1:196
	ds_read2_b64 v[46:49], v85 offset0:128 offset1:132
	v_cvt_pk_bf16_f32 v50, v57, v65
	v_cvt_pk_bf16_f32 v51, v67, v68
	v_cvt_pk_bf16_f32 v52, v69, v70
	v_cvt_pk_bf16_f32 v53, v71, v72
	ds_read2_b64 v[54:57], v63 offset0:72 offset1:76
	v_sub_f32_e32 v27, v24, v66
	s_waitcnt lgkmcnt(4)
	v_mfma_f32_16x16x32_bf16 v[34:37], v[34:37], v[30:33], 0
	v_exp_f32_e32 v27, v27
	v_cmp_lt_f32_e32 vcc, s92, v24
	v_add_f32_e32 v26, v83, v26
	s_waitcnt lgkmcnt(3)
	v_mfma_f32_16x16x32_bf16 v[38:41], v[38:41], v[30:33], 0
	v_cndmask_b32_e32 v65, 0, v27, vcc
	v_add_f32_e32 v24, v65, v26
	v_sub_f32_e32 v26, v25, v66
	s_waitcnt lgkmcnt(2)
	v_mfma_f32_16x16x32_bf16 v[42:45], v[42:45], v[30:33], 0
	v_exp_f32_e32 v26, v26
	v_cmp_lt_f32_e32 vcc, s92, v25
	v_sub_f32_e32 v69, v22, v66
	s_waitcnt lgkmcnt(1)
; #define LAS __attribute__((address_space(3)))
; __device__ __forceinline__ unsigned pk2(float lo, float hi) { return pg8::cvt_pk_bf16(lo, hi); }
; __device__ __forceinline__ void attn_sample_unit(const Args& a, LAS unsigned char* lds, int l, int b, int kvh, int tid) {
;     ...
;         for (int st = 0; st < NKP / 32; ++st) {
;             u32x4 w; w.x = pk2(S[2 * st][0], S[2 * st][1]); w.y = pk2(S[2 * st][2], S[2 * st][3]); w.z = pk2(S[2 * st + 1][0], S[2 * st + 1][1]); w.w = pk2(S[2 * st + 1][2], S[2 * st + 1][3]);
;             const bf16x8 pf = __builtin_bit_cast(bf16x8, w);
; #pragma unroll
;             for (int dt = 0; dt < 4; ++dt) { const u32x2 lo = *(const LAS u32x2*)(Vt + (dt * 16 + r) * VST + 32 * st + 4 * qd), hi = *(const LAS u32x2*)(Vt + (dt * 16 + r) * VST + 32 * st + 16 + 4 * qd);
;                 O[dt] = __builtin_amdgcn_mfma_f32_16x16x32_bf16(__builtin_bit_cast(bf16x8, (u32x4){lo.x, lo.y, hi.x, hi.y}), pf, O[dt], 0, 0, 0); }
;         }
;         lsum += __shfl_xor(lsum, 16); lsum += __shfl_xor(lsum, 32);
;         const float inv = __builtin_amdgcn_rcpf(lsum + __builtin_amdgcn_exp2f(sinkl - mx));
;         bf16_t* op = (bf16_t*)(a.ws + WS_B) + (zrow0 + t) * 512 + h * 64 + 4 * qd;
; #pragma unroll
;         for (int dt = 0; dt < 4; ++dt) { u32x2 w; w.x = pk2(O[dt][0] * inv, O[dt][1] * inv); w.y = pk2(O[dt][2] * inv, O[dt][3] * inv); *(u32x2*)(op + dt * 16) = w; }
	v_mfma_f32_16x16x32_bf16 v[30:33], v[46:49], v[30:33], 0
	ds_read2_b64 v[46:49], v82 offset0:8 offset1:12
	v_cndmask_b32_e32 v67, 0, v26, vcc
	v_add_f32_e32 v68, v67, v24
	s_waitcnt lgkmcnt(1)
	v_mfma_f32_16x16x32_bf16 v[34:37], v[54:57], v[50:53], v[34:37]
	ds_read2_b64 v[54:57], v84 offset0:200 offset1:204
	v_exp_f32_e32 v69, v69
	v_cmp_lt_f32_e32 vcc, s92, v22
	s_waitcnt lgkmcnt(1)
	v_mfma_f32_16x16x32_bf16 v[24:27], v[46:49], v[50:53], v[38:41]
	v_sub_f32_e32 v22, v20, v66
	s_nop 1
	v_sub_f32_e32 v38, v23, v66
	v_exp_f32_e32 v70, v38
	s_waitcnt lgkmcnt(0)
	v_mfma_f32_16x16x32_bf16 v[38:41], v[54:57], v[50:53], v[42:45]
	v_exp_f32_e32 v22, v22
	v_cndmask_b32_e32 v69, 0, v69, vcc
	v_cmp_lt_f32_e32 vcc, s92, v23
	ds_read2_b64 v[42:45], v85 offset0:136 offset1:140
	v_cvt_pk_bf16_f32 v46, v73, v74
	v_cvt_pk_bf16_f32 v47, v75, v76
	v_cvt_pk_bf16_f32 v48, v77, v78
	v_cvt_pk_bf16_f32 v49, v79, v80
	ds_read2_b64 v[54:57], v63 offset0:80 offset1:84
	s_waitcnt lgkmcnt(1)
	v_mfma_f32_16x16x32_bf16 v[30:33], v[42:45], v[50:53], v[30:33]
	ds_read2_b64 v[42:45], v82 offset0:16 offset1:20
	v_cndmask_b32_e32 v70, 0, v70, vcc
	v_sub_f32_e32 v23, v21, v66
	ds_read2_b64 v[50:53], v84 offset0:208 offset1:212
	v_cmp_lt_f32_e32 vcc, s92, v20
	s_waitcnt lgkmcnt(2)
	v_mfma_f32_16x16x32_bf16 v[34:37], v[54:57], v[46:49], v[34:37]
	v_exp_f32_e32 v54, v23
	v_cndmask_b32_e32 v71, 0, v22, vcc
	v_sub_f32_e32 v20, v59, v66
	s_waitcnt lgkmcnt(1)
	v_mfma_f32_16x16x32_bf16 v[22:25], v[42:45], v[46:49], v[24:27]
	ds_read2_b64 v[42:45], v85 offset0:144 offset1:148
	v_exp_f32_e32 v20, v20
	v_cmp_lt_f32_e32 vcc, s92, v21
	s_waitcnt lgkmcnt(1)
	v_mfma_f32_16x16x32_bf16 v[38:41], v[50:53], v[46:49], v[38:41]
	v_cvt_pk_bf16_f32 v50, v81, v83
	v_cvt_pk_bf16_f32 v51, v65, v67
	v_cvt_pk_bf16_f32 v52, v69, v70
	s_waitcnt lgkmcnt(0)
	v_mfma_f32_16x16x32_bf16 v[30:33], v[42:45], v[46:49], v[30:33]
	v_cndmask_b32_e32 v72, 0, v54, vcc
	v_cmp_lt_f32_e32 vcc, s92, v59
	v_cvt_pk_bf16_f32 v53, v71, v72
	ds_read2_b64 v[54:57], v63 offset0:88 offset1:92
	ds_read2_b64 v[42:45], v82 offset0:24 offset1:28
	v_cndmask_b32_e32 v59, 0, v20, vcc
	v_sub_f32_e32 v20, v64, v66
	v_exp_f32_e32 v20, v20
	ds_read2_b64 v[46:49], v84 offset0:216 offset1:220
	v_cmp_lt_f32_e32 vcc, s92, v64
	s_waitcnt lgkmcnt(2)
	v_mfma_f32_16x16x32_bf16 v[34:37], v[54:57], v[50:53], v[34:37]
	v_cndmask_b32_e32 v64, 0, v20, vcc
	v_sub_f32_e32 v20, v62, v66
	v_exp_f32_e32 v26, v20
	v_sub_f32_e32 v20, v58, v66
	v_exp_f32_e32 v27, v20
	v_cmp_lt_f32_e32 vcc, s92, v62
	s_waitcnt lgkmcnt(1)
	v_mfma_f32_16x16x32_bf16 v[20:23], v[42:45], v[50:53], v[22:25]
	v_add_f32_e32 v56, v69, v68
	v_cndmask_b32_e32 v54, 0, v26, vcc
	v_cmp_lt_f32_e32 vcc, s92, v58
	v_add_f32_e32 v56, v70, v56
	v_add_f32_e32 v56, v71, v56
	v_cndmask_b32_e32 v55, 0, v27, vcc
	s_waitcnt lgkmcnt(0)
	v_mfma_f32_16x16x32_bf16 v[24:27], v[46:49], v[50:53], v[38:41]
	v_exp_f32_e32 v0, v0
	s_nop 1
	ds_read2_b64 v[38:41], v85 offset0:152 offset1:156
	v_cvt_pk_bf16_f32 v42, v59, v64
	v_cvt_pk_bf16_f32 v43, v54, v55
	v_cvt_pk_bf16_f32 v44, v1, v1
	v_cvt_pk_bf16_f32 v45, v1, v1
	ds_read2_b64 v[46:49], v63 offset0:96 offset1:100
	s_waitcnt lgkmcnt(1)
	v_mfma_f32_16x16x32_bf16 v[30:33], v[38:41], v[50:53], v[30:33]
	ds_read2_b64 v[38:41], v82 offset0:32 offset1:36
	v_add_f32_e32 v50, v72, v56
	v_add_f32_e32 v50, v59, v50
	v_add_f32_e32 v50, v64, v50
	s_waitcnt lgkmcnt(1)
	v_mfma_f32_16x16x32_bf16 v[34:37], v[46:49], v[42:45], v[34:37]
	ds_read2_b64 v[46:49], v84 offset0:224 offset1:228
	v_add_f32_e32 v50, v54, v50
	v_add_f32_e32 v50, v55, v50
	v_add_f32_e32 v50, 0, v50
	ds_bpermute_b32 v28, v28, v50
	s_waitcnt lgkmcnt(2)
	v_mfma_f32_16x16x32_bf16 v[20:23], v[38:41], v[42:45], v[20:23]
	ds_read2_b64 v[38:41], v85 offset0:160 offset1:164
	s_waitcnt lgkmcnt(2)
	v_mfma_f32_16x16x32_bf16 v[24:27], v[46:49], v[42:45], v[24:27]
	s_waitcnt lgkmcnt(1)
	v_add_f32_e32 v46, v50, v28
	ds_bpermute_b32 v47, v29, v46
	s_waitcnt lgkmcnt(1)
	v_mfma_f32_16x16x32_bf16 v[28:31], v[38:41], v[42:45], v[30:33]
	s_waitcnt lgkmcnt(0)
	s_nop 1
	v_add_f32_e32 v32, v46, v47
	v_add_f32_e32 v0, v0, v32
	v_rcp_f32_e32 v38, v0
	v_lshlrev_b32_e32 v0, 1, v61
	v_lshl_add_u64 v[2:3], v[2:3], 0, v[0:1]
	v_mov_b32_e32 v61, v1
	v_mul_f32_e32 v0, v34, v38
	v_mul_f32_e32 v32, v35, v38
	v_cvt_pk_bf16_f32 v32, v0, v32
	v_mul_f32_e32 v0, v36, v38
	v_mul_f32_e32 v33, v37, v38
	v_lshl_add_u64 v[2:3], v[2:3], 0, v[60:61]
	v_cvt_pk_bf16_f32 v33, v0, v33
	v_mul_f32_e32 v0, v20, v38
	v_mul_f32_e32 v20, v21, v38
	v_mul_f32_e32 v21, v23, v38
	global_store_dwordx2 v[2:3], v[32:33], off
	v_cvt_pk_bf16_f32 v20, v0, v20
	v_mul_f32_e32 v0, v22, v38
	v_cvt_pk_bf16_f32 v21, v0, v21
	global_store_dwordx2 v[2:3], v[20:21], off offset:32
	v_mul_f32_e32 v0, v24, v38
	v_mul_f32_e32 v20, v25, v38
	v_mul_f32_e32 v21, v27, v38
	v_cvt_pk_bf16_f32 v20, v0, v20
	v_mul_f32_e32 v0, v26, v38
	v_cvt_pk_bf16_f32 v21, v0, v21
	global_store_dwordx2 v[2:3], v[20:21], off offset:64
	v_mul_f32_e32 v0, v28, v38
	v_mul_f32_e32 v20, v29, v38
	v_mul_f32_e32 v21, v31, v38
	v_cvt_pk_bf16_f32 v20, v0, v20
	v_mul_f32_e32 v0, v30, v38
	v_cvt_pk_bf16_f32 v21, v0, v21
	global_store_dwordx2 v[2:3], v[20:21], off offset:96
	s_branch .LBB0_595
